# 8-column GEMM phases: column tile index rotated by the row-panel index within each 8x8 XCD round (blocks j and j+32 no longer take the same weight tile)
# speedup vs baseline: 1.0029x; 1.0029x over previous
.LBB0_368:
	s_and_b32 s3, s2, 7
	s_lshr_b32 s4, s92, 3
	s_mul_i32 s3, s4, s3
	s_lshr_b32 s4, s2, 3
	s_lshr_b32 vcc_lo, s4, 3
	s_add_u32 vcc_lo, vcc_lo, s4
	s_and_b32 vcc_lo, vcc_lo, 7
	s_andn2_b32 s4, s4, 7
	s_or_b32 s4, s4, vcc_lo
	s_add_i32 s3, s3, s4
	s_cmpk_gt_i32 s3, 0x7ff
	s_cbranch_scc1 .LBB0_381

.LBB0_490:
	s_and_b32 s3, s2, 7
	s_lshr_b32 s4, s92, 3
	s_mul_i32 s3, s4, s3
	s_lshr_b32 s4, s2, 3
	s_lshr_b32 vcc_lo, s4, 3
	s_add_u32 vcc_lo, vcc_lo, s4
	s_and_b32 vcc_lo, vcc_lo, 7
	s_andn2_b32 s4, s4, 7
	s_or_b32 s4, s4, vcc_lo
	s_add_i32 s64, s3, s4
	s_add_u32 s3, s26, 0x1200000
	s_addc_u32 s86, s27, 0
	s_cmpk_gt_i32 s64, 0x7ff
	s_cbranch_scc1 .LBB0_503

.LBB0_835:
	s_and_b32 s4, s2, 7
	s_lshr_b32 s5, s92, 3
	s_mul_i32 s4, s5, s4
	s_lshr_b32 s5, s2, 3
	s_lshr_b32 vcc_lo, s5, 3
	s_add_u32 vcc_lo, vcc_lo, s5
	s_and_b32 vcc_lo, vcc_lo, 7
	s_andn2_b32 s5, s5, 7
	s_or_b32 s5, s5, vcc_lo
	s_add_i32 s10, s4, s5
	s_cmpk_gt_i32 s10, 0x7ff
	s_cbranch_scc1 .LBB0_848

.LBB0_957:
	s_and_b32 s0, s2, 7
	s_lshr_b32 s1, s92, 3
	s_mul_i32 s0, s1, s0
	s_lshr_b32 s1, s2, 3
	s_lshr_b32 vcc_lo, s1, 3
	s_add_u32 vcc_lo, vcc_lo, s1
	s_and_b32 vcc_lo, vcc_lo, 7
	s_andn2_b32 s1, s1, 7
	s_or_b32 s1, s1, vcc_lo
	s_add_i32 s2, s0, s1
	s_cmpk_gt_i32 s2, 0x7ff
	s_cbranch_scc1 .LBB0_970
